# plus mixer-B selected-block branch: far constant-bias tiles not selected by every query take a short per-lane-masked path (16 packed adds + 32 selects) instead of the generic per-element distance/bias
# speedup vs baseline: 1.0045x; 1.0045x over previous
.LBB0_1464:
	s_mul_i32 s18, s71, 0x5400
	s_add_i32 s18, s18, 0
	v_add3_u32 v42, s18, v198, v195
	ds_read_b128 v[34:37], v42 offset:4608
	ds_read_b128 v[38:41], v42
	ds_read_b128 v[66:69], v42 offset:32
	ds_read_b128 v[70:73], v42 offset:4640
	ds_read_b128 v[74:77], v42 offset:64
	ds_read_b128 v[78:81], v42 offset:4672
	ds_read_b128 v[82:85], v42 offset:96
	ds_read_b128 v[86:89], v42 offset:4704
	s_waitcnt lgkmcnt(6)
	v_mfma_f32_32x32x16_bf16 v[50:65], v[38:41], v[98:101], 0
	v_mfma_f32_32x32x16_bf16 v[34:49], v[34:37], v[98:101], 0
	s_waitcnt lgkmcnt(5)
	v_mfma_f32_32x32x16_bf16 v[50:65], v[66:69], v[102:105], v[50:65]
	s_waitcnt lgkmcnt(4)
	v_mfma_f32_32x32x16_bf16 v[34:49], v[70:73], v[102:105], v[34:49]
	s_waitcnt lgkmcnt(3)
	v_mfma_f32_32x32x16_bf16 v[50:65], v[74:77], v[106:109], v[50:65]
	v_add_u32_e32 v178, s18, v196
	ds_read_b64_tr_b16 v[126:127], v178 offset:9216
	ds_read_b64_tr_b16 v[128:129], v178 offset:10752
	ds_read_b64_tr_b16 v[122:123], v178 offset:9280
	ds_read_b64_tr_b16 v[124:125], v178 offset:10816
	s_mov_b64 s[18:19], -1
	s_andn2_b64 vcc, exec, s[10:11]
	s_waitcnt lgkmcnt(6)
	v_mfma_f32_32x32x16_bf16 v[34:49], v[78:81], v[106:109], v[34:49]
	s_waitcnt lgkmcnt(5)
	v_mfma_f32_32x32x16_bf16 v[50:65], v[82:85], v[110:113], v[50:65]
	s_waitcnt lgkmcnt(4)
	v_mfma_f32_32x32x16_bf16 v[34:49], v[86:89], v[110:113], v[34:49]
	s_cbranch_vccz .LBB0_1500
	s_andn2_b64 vcc, exec, s[16:17]
	s_cbranch_vccnz .Lslc_farmask
	v_subrev_u32_e32 v68, s75, v193
	v_cndmask_b32_e64 v67, 0, 1, s[16:17]
	v_add_u32_e32 v66, v68, v203
	v_cmp_ne_u32_e64 s[10:11], 1, v67
	s_andn2_b64 vcc, exec, s[16:17]
	v_mov_b32_e32 v67, v174
	s_cbranch_vccnz .LBB0_1467
	v_med3_i32 v67, v66, 0, v192
	v_lshl_add_u32 v67, v67, 2, s3
	ds_read_b32 v67, v67

.Lslc_farmask:
	s_nop 6
	v_pk_add_f32 v[80:81], v[174:175], v[64:65] op_sel_hi:[0,1]
	v_pk_add_f32 v[78:79], v[174:175], v[62:63] op_sel_hi:[0,1]
	v_pk_add_f32 v[76:77], v[174:175], v[60:61] op_sel_hi:[0,1]
	v_pk_add_f32 v[74:75], v[174:175], v[58:59] op_sel_hi:[0,1]
	v_pk_add_f32 v[72:73], v[174:175], v[56:57] op_sel_hi:[0,1]
	v_pk_add_f32 v[70:71], v[174:175], v[54:55] op_sel_hi:[0,1]
	v_pk_add_f32 v[68:69], v[174:175], v[52:53] op_sel_hi:[0,1]
	v_pk_add_f32 v[66:67], v[174:175], v[50:51] op_sel_hi:[0,1]
	v_pk_add_f32 v[96:97], v[174:175], v[48:49] op_sel_hi:[0,1]
	v_pk_add_f32 v[94:95], v[174:175], v[46:47] op_sel_hi:[0,1]
	v_pk_add_f32 v[92:93], v[174:175], v[44:45] op_sel_hi:[0,1]
	v_pk_add_f32 v[90:91], v[174:175], v[42:43] op_sel_hi:[0,1]
	v_pk_add_f32 v[88:89], v[174:175], v[40:41] op_sel_hi:[0,1]
	v_pk_add_f32 v[86:87], v[174:175], v[38:39] op_sel_hi:[0,1]
	v_pk_add_f32 v[84:85], v[174:175], v[36:37] op_sel_hi:[0,1]
	v_pk_add_f32 v[82:83], v[174:175], v[34:35] op_sel_hi:[0,1]
	s_mov_b64 vcc, s[8:9]
	v_cndmask_b32_e32 v66, v191, v66, vcc
	v_cndmask_b32_e32 v67, v191, v67, vcc
	v_cndmask_b32_e32 v68, v191, v68, vcc
	v_cndmask_b32_e32 v69, v191, v69, vcc
	v_cndmask_b32_e32 v70, v191, v70, vcc
	v_cndmask_b32_e32 v71, v191, v71, vcc
	v_cndmask_b32_e32 v72, v191, v72, vcc
	v_cndmask_b32_e32 v73, v191, v73, vcc
	v_cndmask_b32_e32 v74, v191, v74, vcc
	v_cndmask_b32_e32 v75, v191, v75, vcc
	v_cndmask_b32_e32 v76, v191, v76, vcc
	v_cndmask_b32_e32 v77, v191, v77, vcc
	v_cndmask_b32_e32 v78, v191, v78, vcc
	v_cndmask_b32_e32 v79, v191, v79, vcc
	v_cndmask_b32_e32 v80, v191, v80, vcc
	v_cndmask_b32_e32 v81, v191, v81, vcc
	v_cndmask_b32_e32 v82, v191, v82, vcc
	v_cndmask_b32_e32 v83, v191, v83, vcc
	v_cndmask_b32_e32 v84, v191, v84, vcc
	v_cndmask_b32_e32 v85, v191, v85, vcc
	v_cndmask_b32_e32 v86, v191, v86, vcc
	v_cndmask_b32_e32 v87, v191, v87, vcc
	v_cndmask_b32_e32 v88, v191, v88, vcc
	v_cndmask_b32_e32 v89, v191, v89, vcc
	v_cndmask_b32_e32 v90, v191, v90, vcc
	v_cndmask_b32_e32 v91, v191, v91, vcc
	v_cndmask_b32_e32 v92, v191, v92, vcc
	v_cndmask_b32_e32 v93, v191, v93, vcc
	v_cndmask_b32_e32 v94, v191, v94, vcc
	v_cndmask_b32_e32 v95, v191, v95, vcc
	v_cndmask_b32_e32 v96, v191, v96, vcc
	v_cndmask_b32_e32 v97, v191, v97, vcc
	s_branch .LBB0_1502
